# attention loop waitcnt placement: dropped vmcnt waits that fenced register reuse but stalled on just-issued next-unit loads and O store acks; lse row loaded first, counted vmcnt(4)/(3) for merge
# speedup vs baseline: 1.0040x; 1.0040x over previous
.Lqk_fast:
	s_mov_b64 s[6:7], -1
	s_mov_b64 s[10:11], -1
	s_mov_b64 s[12:13], -1
	s_mov_b64 s[14:15], -1
	s_mov_b64 s[36:37], s[74:75]
	ds_read_b128 v[82:85], v221
	ds_read_b128 v[86:89], v222
	ds_read_b128 v[90:93], v223
	ds_read_b128 v[94:97], v224
	ds_read_b128 v[98:101], v221 offset:4096
	ds_read_b128 v[102:105], v222 offset:4096
	ds_read_b128 v[106:109], v223 offset:4096
	ds_read_b128 v[110:113], v224 offset:4096
	s_waitcnt lgkmcnt(7)
	v_mfma_f32_32x32x16_bf16 v[50:65], v[82:85], v[130:133], 0
	s_waitcnt lgkmcnt(6)
	v_mfma_f32_32x32x16_bf16 v[50:65], v[86:89], v[134:137], v[50:65]
	s_waitcnt lgkmcnt(5)
	v_mfma_f32_32x32x16_bf16 v[50:65], v[90:93], v[138:141], v[50:65]
	s_waitcnt lgkmcnt(4)
	v_mfma_f32_32x32x16_bf16 v[50:65], v[94:97], v[142:145], v[50:65]
	ds_read_b128 v[82:85], v221 offset:8192
	ds_read_b128 v[86:89], v222 offset:8192
	ds_read_b128 v[90:93], v223 offset:8192
	ds_read_b128 v[94:97], v224 offset:8192
	s_waitcnt lgkmcnt(7)
	v_mfma_f32_32x32x16_bf16 v[2:17], v[98:101], v[130:133], 0
	s_waitcnt lgkmcnt(6)
	v_mfma_f32_32x32x16_bf16 v[2:17], v[102:105], v[134:137], v[2:17]
	s_waitcnt lgkmcnt(5)
	v_mfma_f32_32x32x16_bf16 v[2:17], v[106:109], v[138:141], v[2:17]
	s_waitcnt lgkmcnt(4)
	v_mfma_f32_32x32x16_bf16 v[2:17], v[110:113], v[142:145], v[2:17]
	ds_read_b128 v[98:101], v221 offset:12288
	ds_read_b128 v[102:105], v222 offset:12288
	ds_read_b128 v[106:109], v223 offset:12288
	ds_read_b128 v[110:113], v224 offset:12288
	s_waitcnt lgkmcnt(7)
	v_mfma_f32_32x32x16_bf16 v[34:49], v[82:85], v[130:133], 0
	s_waitcnt lgkmcnt(6)
	v_mfma_f32_32x32x16_bf16 v[34:49], v[86:89], v[134:137], v[34:49]
	s_waitcnt lgkmcnt(5)
	v_mfma_f32_32x32x16_bf16 v[34:49], v[90:93], v[138:141], v[34:49]
	s_waitcnt lgkmcnt(4)
	v_mfma_f32_32x32x16_bf16 v[34:49], v[94:97], v[142:145], v[34:49]
	ds_read_b128 v[82:85], v221 offset:16384
	ds_read_b128 v[86:89], v222 offset:16384
	ds_read_b128 v[90:93], v223 offset:16384
	ds_read_b128 v[94:97], v224 offset:16384
	s_waitcnt lgkmcnt(7)
	v_mfma_f32_32x32x16_bf16 v[18:33], v[98:101], v[130:133], 0
	s_waitcnt lgkmcnt(6)
	v_mfma_f32_32x32x16_bf16 v[18:33], v[102:105], v[134:137], v[18:33]
	s_waitcnt lgkmcnt(5)
	v_mfma_f32_32x32x16_bf16 v[18:33], v[106:109], v[138:141], v[18:33]
	s_waitcnt lgkmcnt(4)
	v_mfma_f32_32x32x16_bf16 v[18:33], v[110:113], v[142:145], v[18:33]
	s_waitcnt lgkmcnt(3)
	v_mfma_f32_32x32x16_bf16 v[66:81], v[82:85], v[130:133], 0
	s_waitcnt lgkmcnt(2)
	v_mfma_f32_32x32x16_bf16 v[66:81], v[86:89], v[134:137], v[66:81]
	s_waitcnt lgkmcnt(1)
	v_mfma_f32_32x32x16_bf16 v[66:81], v[90:93], v[138:141], v[66:81]
	s_waitcnt lgkmcnt(0)
	v_mfma_f32_32x32x16_bf16 v[66:81], v[94:97], v[142:145], v[66:81]
	s_branch .LBB0_174

.LBB0_164:
	s_lshl_b32 s25, s22, 8
	s_add_i32 s25, s25, s23
	s_ashr_i32 s6, s25, 5
	s_sub_i32 s6, 4, s6
	s_cmpk_lt_i32 s25, 0x80
	s_cselect_b32 s19, s6, 0
	s_cmp_lt_i32 s19, 1
	s_cselect_b64 s[76:77], -1, 0
	s_cmp_eq_u32 s19, 0
	s_cbranch_scc1 .Lqk_fast
	s_cmp_gt_i32 s19, 0
	s_cbranch_scc1 .Lattn_neg0
	ds_read_b128 v[4:7], v221
	s_waitcnt lgkmcnt(0)
	v_mfma_f32_32x32x16_bf16 v[50:65], v[4:7], v[130:133], 0
	ds_read_b128 v[4:7], v222
	s_waitcnt lgkmcnt(0)
	v_mfma_f32_32x32x16_bf16 v[50:65], v[4:7], v[134:137], v[50:65]
	ds_read_b128 v[4:7], v223
	s_waitcnt lgkmcnt(0)
	v_mfma_f32_32x32x16_bf16 v[50:65], v[4:7], v[138:141], v[50:65]
	ds_read_b128 v[4:7], v224
	s_waitcnt lgkmcnt(0)
	v_mfma_f32_32x32x16_bf16 v[50:65], v[4:7], v[142:145], v[50:65]
.LBB0_166:
	s_cmp_lt_i32 s19, 2
	s_cselect_b64 s[6:7], -1, 0
	s_cmp_gt_i32 s19, 1
	s_cbranch_scc1 .Lattn_neg1
	ds_read_b128 v[2:5], v221 offset:4096
	ds_read_b128 v[18:21], v222 offset:4096
	s_waitcnt lgkmcnt(1)
	v_mfma_f32_32x32x16_bf16 v[2:17], v[2:5], v[130:133], 0
	s_waitcnt lgkmcnt(0)
	v_mfma_f32_32x32x16_bf16 v[2:17], v[18:21], v[134:137], v[2:17]
	ds_read_b128 v[18:21], v223 offset:4096
	s_waitcnt lgkmcnt(0)
	v_mfma_f32_32x32x16_bf16 v[2:17], v[18:21], v[138:141], v[2:17]
	ds_read_b128 v[18:21], v224 offset:4096
	s_waitcnt lgkmcnt(0)
	v_mfma_f32_32x32x16_bf16 v[2:17], v[18:21], v[142:145], v[2:17]
.LBB0_168:
	s_cmp_lt_i32 s19, 3
	s_cselect_b64 s[10:11], -1, 0
	s_cmp_gt_i32 s19, 2
	s_cbranch_scc1 .Lattn_neg2
	ds_read_b128 v[20:23], v221 offset:8192
	s_waitcnt lgkmcnt(0)
	v_mfma_f32_32x32x16_bf16 v[34:49], v[20:23], v[130:133], 0
	ds_read_b128 v[20:23], v222 offset:8192
	s_waitcnt lgkmcnt(0)
	v_mfma_f32_32x32x16_bf16 v[34:49], v[20:23], v[134:137], v[34:49]
	ds_read_b128 v[20:23], v223 offset:8192
	s_waitcnt lgkmcnt(0)
	v_mfma_f32_32x32x16_bf16 v[34:49], v[20:23], v[138:141], v[34:49]
	ds_read_b128 v[20:23], v224 offset:8192
	s_waitcnt lgkmcnt(0)
	v_mfma_f32_32x32x16_bf16 v[34:49], v[20:23], v[142:145], v[34:49]
.LBB0_170:
	s_cmp_lt_i32 s19, 4
	s_cselect_b64 s[12:13], -1, 0
	s_cmp_gt_i32 s19, 3
	s_cbranch_scc1 .Lattn_neg3
	ds_read_b128 v[18:21], v221 offset:12288
	ds_read_b128 v[66:69], v222 offset:12288
	s_waitcnt lgkmcnt(1)
	v_mfma_f32_32x32x16_bf16 v[18:33], v[18:21], v[130:133], 0
	s_waitcnt lgkmcnt(0)
	v_mfma_f32_32x32x16_bf16 v[18:33], v[66:69], v[134:137], v[18:33]
	ds_read_b128 v[66:69], v223 offset:12288
	s_waitcnt lgkmcnt(0)
	v_mfma_f32_32x32x16_bf16 v[18:33], v[66:69], v[138:141], v[18:33]
	ds_read_b128 v[66:69], v224 offset:12288
	s_waitcnt lgkmcnt(0)
	v_mfma_f32_32x32x16_bf16 v[18:33], v[66:69], v[142:145], v[18:33]
.LBB0_172:
	s_cmp_lt_i32 s19, 5
	s_mov_b64 s[36:37], s[74:75]
	s_cselect_b64 s[14:15], -1, 0
	s_cmp_gt_i32 s19, 4
	s_cbranch_scc1 .Lattn_neg4
	ds_read_b128 v[66:69], v221 offset:16384
	ds_read_b128 v[236:239], v222 offset:16384
	s_waitcnt lgkmcnt(1)
	v_mfma_f32_32x32x16_bf16 v[66:81], v[66:69], v[130:133], 0
	s_waitcnt lgkmcnt(0)
	v_mfma_f32_32x32x16_bf16 v[66:81], v[236:239], v[134:137], v[66:81]
	ds_read_b128 v[236:239], v223 offset:16384
	s_waitcnt lgkmcnt(0)
	v_mfma_f32_32x32x16_bf16 v[66:81], v[236:239], v[138:141], v[66:81]
	ds_read_b128 v[236:239], v224 offset:16384
	s_waitcnt lgkmcnt(0)
	v_mfma_f32_32x32x16_bf16 v[66:81], v[236:239], v[142:145], v[66:81]
.LBB0_174:
	s_add_i32 s24, s26, s98
	s_cmpk_lt_i32 s24, 0x400
	s_cselect_b64 s[74:75], -1, 0
	s_cmpk_gt_i32 s24, 0x3ff
	s_cselect_b64 s[92:93], -1, 0
	s_and_b64 vcc, exec, s[92:93]
	s_cbranch_vccnz .LBB0_188
	s_and_b32 s21, s24, 15
	v_readlane_b32 s19, v255, 37
	s_lshr_b32 s19, s21, s19
	v_readlane_b32 s27, v255, 1
	s_lshl_b32 s27, s19, s27
	s_sub_i32 s27, s21, s27
	s_lshl_b32 s21, s24, 4
	s_lshl_b32 s34, s27, 8
	s_bfe_u32 s29, s24, 0x40004
	s_and_b32 s31, s21, 0xfffff000
	v_add_u32_e32 v1, s34, v163
	s_lshl_b32 s21, s29, 6
	s_or_b32 s35, s31, s19
	v_cmp_lt_i32_e32 vcc, -1, v1
	s_and_saveexec_b64 s[72:73], vcc
	s_cbranch_execz .LBB0_177
	v_lshlrev_b32_e32 v82, s43, v1
	v_add_lshl_u32 v82, v82, s35, 10
	v_or3_b32 v82, v82, v164, s21
	v_mov_b32_e32 v83, v0
	v_lshl_add_u64 v[82:83], v[82:83], 1, s[4:5]
	global_load_dwordx4 v[82:85], v[82:83], off
.LBB0_177:
	s_or_b64 exec, exec, s[72:73]
	s_movk_i32 s72, 0xffbf
	v_cmp_lt_i32_e32 vcc, s72, v1
	s_and_saveexec_b64 s[72:73], vcc
	s_cbranch_execz .LBB0_179
	v_add_lshl_u32 v86, v1, 64, s43
	v_add_lshl_u32 v86, v86, s35, 10
	v_or3_b32 v86, v86, v164, s21
	v_mov_b32_e32 v87, v0
	v_lshl_add_u64 v[86:87], v[86:87], 1, s[4:5]
	global_load_dwordx4 v[86:89], v[86:87], off
.LBB0_179:
	s_or_b64 exec, exec, s[72:73]
	v_add_u32_e32 v130, s34, v162
	v_cmp_lt_i32_e32 vcc, -1, v130
	s_and_saveexec_b64 s[72:73], vcc
	s_cbranch_execz .LBB0_181
	v_lshlrev_b32_e32 v90, s43, v130
	v_add_lshl_u32 v90, v90, s35, 10
	v_or3_b32 v90, v90, v164, s21
	v_mov_b32_e32 v91, v0
	v_lshl_add_u64 v[90:91], v[90:91], 1, s[4:5]
	global_load_dwordx4 v[90:93], v[90:91], off

.LBB0_187:
	s_or_b64 exec, exec, s[72:73]
	v_add_u32_e32 v1, s34, v179
	v_lshlrev_b32_e32 v1, s43, v1
	v_add_lshl_u32 v1, v1, s35, 10
	v_readlane_b32 s34, v255, 3
	v_or3_b32 v130, v1, v166, s21
	v_mov_b32_e32 v131, v0
	v_readlane_b32 s35, v255, 4
	v_lshl_add_u64 v[142:143], v[130:131], 1, s[34:35]
	global_load_dwordx4 v[130:133], v[142:143], off
	global_load_dwordx4 v[134:137], v[142:143], off offset:32
	global_load_dwordx4 v[138:141], v[142:143], off offset:64
	s_nop 0
	global_load_dwordx4 v[142:145], v[142:143], off offset:96
	s_branch .LBB0_189

.LBB0_189:
	v_readlane_b32 s34, v255, 11
	v_readlane_b32 s35, v255, 12
	v_cndmask_b32_e64 v1, v50, v232, s[8:9]
	v_cndmask_b32_e64 v58, v58, v232, s[40:41]
	v_cndmask_b32_e64 v50, v66, v232, s[34:35]
	v_readlane_b32 s34, v255, 13
	v_readlane_b32 s35, v255, 14
	v_cndmask_b32_e64 v50, v50, v66, s[8:9]
	v_cndmask_b32_e64 v59, v59, v232, s[44:45]
	v_cndmask_b32_e64 v51, v51, v232, s[34:35]
	v_readlane_b32 s34, v255, 15
	v_readlane_b32 s35, v255, 16
	v_cndmask_b32_e64 v60, v60, v232, s[48:49]
	v_cndmask_b32_e64 v61, v61, v232, s[52:53]
	v_cndmask_b32_e64 v52, v52, v232, s[34:35]
	v_readlane_b32 s34, v255, 17
	v_readlane_b32 s35, v255, 18
	v_cndmask_b32_e64 v62, v62, v232, s[56:57]
	v_cndmask_b32_e64 v63, v63, v232, s[60:61]
	v_cndmask_b32_e64 v66, v68, v232, s[34:35]
	v_readlane_b32 s34, v255, 19
	v_readlane_b32 s35, v255, 20
	v_cndmask_b32_e64 v64, v64, v232, s[64:65]
	v_cndmask_b32_e64 v65, v65, v232, s[68:69]
	v_cndmask_b32_e64 v53, v53, v232, s[34:35]
	v_readlane_b32 s34, v255, 21
	v_readlane_b32 s35, v255, 22
	v_cndmask_b32_e64 v67, v232, v67, s[8:9]
	s_andn2_b64 vcc, exec, s[74:75]
	v_cndmask_b32_e64 v68, v69, v232, s[34:35]
	v_readlane_b32 s34, v255, 23
	v_readlane_b32 s35, v255, 24
	s_nop 1
	v_cndmask_b32_e64 v54, v54, v232, s[34:35]
	v_readlane_b32 s34, v255, 25
	v_readlane_b32 s35, v255, 26
	s_nop 1
	v_cndmask_b32_e64 v69, v70, v232, s[34:35]
	v_readlane_b32 s34, v255, 27
	v_readlane_b32 s35, v255, 28
	s_nop 1
	v_cndmask_b32_e64 v55, v55, v232, s[34:35]
	v_readlane_b32 s34, v255, 29
	v_readlane_b32 s35, v255, 30
	s_nop 1
	v_cndmask_b32_e64 v70, v71, v232, s[34:35]
	v_readlane_b32 s34, v255, 31
	v_readlane_b32 s35, v255, 32
	s_nop 1
	v_cndmask_b32_e64 v56, v56, v232, s[34:35]
	v_readlane_b32 s34, v255, 33
	v_readlane_b32 s35, v255, 34
	s_nop 1
	v_cndmask_b32_e64 v71, v72, v232, s[34:35]
	v_readlane_b32 s34, v255, 35
	v_readlane_b32 s35, v255, 36
	v_cndmask_b32_e64 v72, v73, v232, s[38:39]
	v_cndmask_b32_e64 v73, v74, v232, s[16:17]
	v_cndmask_b32_e64 v57, v57, v232, s[34:35]
	s_mov_b32 s34, 0xf149f2ca
	v_cndmask_b32_e64 v74, v75, v232, s[46:47]
	v_cndmask_b32_e64 v75, v76, v232, s[50:51]
	v_cndmask_b32_e64 v76, v77, v232, s[54:55]
	v_cndmask_b32_e64 v77, v78, v232, s[58:59]
	v_cndmask_b32_e64 v78, v79, v232, s[62:63]
	v_cndmask_b32_e64 v79, v80, v232, s[66:67]
	v_cndmask_b32_e64 v80, v81, v232, s[70:71]
	v_max3_f32 v81, v1, s34, v51
	v_max3_f32 v81, v81, v52, v53
	v_max3_f32 v81, v81, v54, v55
	v_max3_f32 v81, v81, v56, v57
	v_max3_f32 v81, v81, v58, v59
	v_max3_f32 v81, v81, v60, v61
	v_max3_f32 v81, v81, v62, v63
	v_max3_f32 v81, v81, v64, v65
	v_max3_f32 v81, v81, v2, v3
	v_max3_f32 v81, v81, v4, v5
	v_max3_f32 v81, v81, v6, v7
	v_max3_f32 v81, v81, v8, v9
	v_max3_f32 v81, v81, v10, v11
	v_max3_f32 v81, v81, v12, v13
	v_max3_f32 v81, v81, v14, v15
	v_max3_f32 v81, v81, v16, v17
	v_max3_f32 v81, v81, v34, v35
	v_max3_f32 v81, v81, v36, v37
	v_max3_f32 v81, v81, v38, v39
	v_max3_f32 v81, v81, v40, v41
	v_max3_f32 v81, v81, v42, v43
	v_max3_f32 v81, v81, v44, v45
	v_max3_f32 v81, v81, v46, v47
	v_max3_f32 v81, v81, v48, v49
	v_max3_f32 v81, v81, v18, v19
	v_max3_f32 v81, v81, v20, v21
	v_max3_f32 v81, v81, v22, v23
	v_max3_f32 v81, v81, v24, v25
	v_max3_f32 v81, v81, v26, v27
	v_max3_f32 v81, v81, v28, v29
	v_max3_f32 v81, v81, v30, v31
	v_max3_f32 v81, v81, v32, v33
	v_max3_f32 v81, v81, v50, v67
	v_max3_f32 v81, v81, v66, v68
	v_max3_f32 v81, v81, v69, v70
	v_max3_f32 v81, v81, v71, v72
	v_max3_f32 v81, v81, v73, v74
	v_max3_f32 v81, v81, v75, v76
	v_max3_f32 v81, v81, v77, v78
	v_max3_f32 v81, v81, v79, v80
	ds_bpermute_b32 v225, v180, v81
	s_waitcnt lgkmcnt(0)
	v_max_f32_e32 v225, v225, v225
	v_max_f32_e32 v81, v81, v225
	v_sub_f32_e32 v1, v1, v81
	v_exp_f32_e32 v1, v1
	v_sub_f32_e32 v51, v51, v81
	v_exp_f32_e32 v51, v51
	v_sub_f32_e32 v52, v52, v81
	v_exp_f32_e32 v52, v52
	v_sub_f32_e32 v53, v53, v81
	v_exp_f32_e32 v53, v53
	v_sub_f32_e32 v54, v54, v81
	v_add_f32_e32 v225, 0, v1
	v_exp_f32_e32 v54, v54
	v_sub_f32_e32 v55, v55, v81
	v_add_f32_e32 v225, v51, v225
	v_exp_f32_e32 v55, v55
	v_sub_f32_e32 v56, v56, v81
	v_add_f32_e32 v225, v52, v225
	v_exp_f32_e32 v56, v56
	v_sub_f32_e32 v57, v57, v81
	v_add_f32_e32 v225, v53, v225
	v_exp_f32_e32 v57, v57
	v_sub_f32_e32 v58, v58, v81
	v_add_f32_e32 v225, v54, v225
	v_exp_f32_e32 v58, v58
	v_sub_f32_e32 v59, v59, v81
	v_add_f32_e32 v225, v55, v225
	v_exp_f32_e32 v59, v59
	v_sub_f32_e32 v60, v60, v81
	v_add_f32_e32 v225, v56, v225
	v_exp_f32_e32 v60, v60
	v_sub_f32_e32 v61, v61, v81
	v_add_f32_e32 v225, v57, v225
	v_exp_f32_e32 v61, v61
	v_sub_f32_e32 v62, v62, v81
	v_add_f32_e32 v225, v58, v225
	v_exp_f32_e32 v62, v62
	v_sub_f32_e32 v63, v63, v81
	v_add_f32_e32 v225, v59, v225
	v_exp_f32_e32 v63, v63
	v_sub_f32_e32 v64, v64, v81
	v_add_f32_e32 v225, v60, v225
	v_exp_f32_e32 v64, v64
	v_sub_f32_e32 v65, v65, v81
	v_add_f32_e32 v225, v61, v225
	v_exp_f32_e32 v65, v65
	v_sub_f32_e32 v2, v2, v81
	v_add_f32_e32 v225, v62, v225
	v_exp_f32_e32 v230, v2
	v_sub_f32_e32 v2, v3, v81
	v_add_f32_e32 v225, v63, v225
	v_exp_f32_e32 v231, v2
	v_sub_f32_e32 v2, v4, v81
	v_add_f32_e32 v225, v64, v225
	v_exp_f32_e32 v237, v2
	v_sub_f32_e32 v2, v5, v81
	v_add_f32_e32 v225, v65, v225
	v_exp_f32_e32 v238, v2
	v_sub_f32_e32 v3, v6, v81
	v_add_f32_e32 v2, v230, v225
	v_exp_f32_e32 v225, v3
	v_sub_f32_e32 v3, v7, v81
	v_add_f32_e32 v2, v231, v2
	v_exp_f32_e32 v239, v3
	v_sub_f32_e32 v3, v8, v81
	v_add_f32_e32 v2, v237, v2
	v_exp_f32_e32 v240, v3
	v_sub_f32_e32 v3, v9, v81
	v_add_f32_e32 v2, v238, v2
	v_exp_f32_e32 v241, v3
	v_sub_f32_e32 v3, v10, v81
	v_add_f32_e32 v2, v225, v2
	v_exp_f32_e32 v10, v3
	v_sub_f32_e32 v3, v11, v81
	v_add_f32_e32 v2, v239, v2
	v_exp_f32_e32 v11, v3
	v_sub_f32_e32 v3, v12, v81
	v_add_f32_e32 v2, v240, v2
	v_exp_f32_e32 v12, v3
	v_sub_f32_e32 v3, v13, v81
	v_add_f32_e32 v2, v241, v2
	v_exp_f32_e32 v13, v3
	v_sub_f32_e32 v3, v14, v81
	v_add_f32_e32 v2, v10, v2
	v_exp_f32_e32 v14, v3
	v_sub_f32_e32 v3, v15, v81
	v_add_f32_e32 v2, v11, v2
	v_exp_f32_e32 v15, v3
	v_sub_f32_e32 v3, v16, v81
	v_add_f32_e32 v2, v12, v2
	v_exp_f32_e32 v16, v3
	v_sub_f32_e32 v3, v17, v81
	v_add_f32_e32 v2, v13, v2
	v_exp_f32_e32 v17, v3
	v_sub_f32_e32 v3, v34, v81
	v_add_f32_e32 v2, v14, v2
	v_exp_f32_e32 v34, v3
	v_sub_f32_e32 v3, v35, v81
	v_add_f32_e32 v2, v15, v2
	v_exp_f32_e32 v35, v3
	v_sub_f32_e32 v3, v36, v81
	v_add_f32_e32 v2, v16, v2
	v_exp_f32_e32 v36, v3
	v_sub_f32_e32 v3, v37, v81
	v_add_f32_e32 v2, v17, v2
	v_exp_f32_e32 v37, v3
	v_sub_f32_e32 v3, v38, v81
	v_add_f32_e32 v2, v34, v2
	v_exp_f32_e32 v38, v3
	v_sub_f32_e32 v3, v39, v81
	v_add_f32_e32 v2, v35, v2
	v_exp_f32_e32 v39, v3
	v_sub_f32_e32 v3, v40, v81
	v_add_f32_e32 v2, v36, v2
	v_exp_f32_e32 v40, v3
	v_sub_f32_e32 v3, v41, v81
	v_add_f32_e32 v2, v37, v2
	v_exp_f32_e32 v41, v3
	v_sub_f32_e32 v3, v42, v81
	v_add_f32_e32 v2, v38, v2
	v_exp_f32_e32 v42, v3
	v_sub_f32_e32 v3, v43, v81
	v_add_f32_e32 v2, v39, v2
	v_exp_f32_e32 v43, v3
	v_sub_f32_e32 v3, v44, v81
	v_add_f32_e32 v2, v40, v2
	v_exp_f32_e32 v44, v3
	v_sub_f32_e32 v3, v45, v81
	v_add_f32_e32 v2, v41, v2
	v_exp_f32_e32 v45, v3
	v_sub_f32_e32 v3, v46, v81
	v_add_f32_e32 v2, v42, v2
	v_exp_f32_e32 v46, v3
	v_sub_f32_e32 v3, v47, v81
	v_add_f32_e32 v2, v43, v2
	v_exp_f32_e32 v47, v3
	v_sub_f32_e32 v3, v48, v81
	v_add_f32_e32 v2, v44, v2
	v_exp_f32_e32 v48, v3
	v_sub_f32_e32 v3, v49, v81
	v_add_f32_e32 v2, v45, v2
	v_exp_f32_e32 v49, v3
	v_sub_f32_e32 v3, v18, v81
	v_add_f32_e32 v2, v46, v2
	v_exp_f32_e32 v18, v3
	v_sub_f32_e32 v3, v19, v81
	v_add_f32_e32 v2, v47, v2
	v_exp_f32_e32 v19, v3
	v_sub_f32_e32 v3, v20, v81
	v_add_f32_e32 v2, v48, v2
	v_exp_f32_e32 v20, v3
	v_sub_f32_e32 v3, v21, v81
	v_add_f32_e32 v2, v49, v2
	v_exp_f32_e32 v21, v3
	v_sub_f32_e32 v3, v22, v81
	v_add_f32_e32 v2, v18, v2
	v_exp_f32_e32 v22, v3
	v_sub_f32_e32 v3, v23, v81
	v_add_f32_e32 v2, v19, v2
	v_exp_f32_e32 v23, v3
	v_sub_f32_e32 v3, v24, v81
	v_add_f32_e32 v2, v20, v2
	v_exp_f32_e32 v24, v3
	v_sub_f32_e32 v3, v25, v81
	v_add_f32_e32 v2, v21, v2
	v_exp_f32_e32 v25, v3
	v_sub_f32_e32 v3, v26, v81
	v_add_f32_e32 v2, v22, v2
	v_exp_f32_e32 v26, v3
	v_sub_f32_e32 v3, v27, v81
	v_add_f32_e32 v2, v23, v2
	v_exp_f32_e32 v27, v3
	v_sub_f32_e32 v3, v28, v81
	v_add_f32_e32 v2, v24, v2
	v_exp_f32_e32 v28, v3
	v_sub_f32_e32 v3, v29, v81
	v_add_f32_e32 v2, v25, v2
	v_exp_f32_e32 v29, v3
	v_sub_f32_e32 v3, v30, v81
	v_add_f32_e32 v2, v26, v2
	v_exp_f32_e32 v30, v3
	v_sub_f32_e32 v3, v31, v81
	v_add_f32_e32 v2, v27, v2
	v_exp_f32_e32 v31, v3
	v_sub_f32_e32 v3, v32, v81
	v_add_f32_e32 v2, v28, v2
	v_exp_f32_e32 v32, v3
	v_sub_f32_e32 v3, v33, v81
	v_add_f32_e32 v2, v29, v2
	v_exp_f32_e32 v33, v3
	v_sub_f32_e32 v3, v50, v81
	v_add_f32_e32 v2, v30, v2
	v_exp_f32_e32 v50, v3
	v_sub_f32_e32 v3, v67, v81
	v_add_f32_e32 v2, v31, v2
	v_exp_f32_e32 v242, v3
	v_sub_f32_e32 v3, v66, v81
	v_add_f32_e32 v2, v32, v2
	v_exp_f32_e32 v243, v3
	v_sub_f32_e32 v3, v68, v81
	v_add_f32_e32 v2, v33, v2
	v_exp_f32_e32 v244, v3
	v_sub_f32_e32 v3, v69, v81
	v_add_f32_e32 v2, v50, v2
	v_exp_f32_e32 v245, v3
	v_sub_f32_e32 v3, v70, v81
	v_add_f32_e32 v2, v242, v2
	v_exp_f32_e32 v246, v3
	v_sub_f32_e32 v3, v71, v81
	v_add_f32_e32 v2, v243, v2
	v_exp_f32_e32 v247, v3
	v_sub_f32_e32 v3, v72, v81
	v_add_f32_e32 v2, v244, v2
	v_exp_f32_e32 v248, v3
	v_sub_f32_e32 v3, v73, v81
	v_add_f32_e32 v2, v245, v2
	v_exp_f32_e32 v249, v3
	v_sub_f32_e32 v3, v74, v81
	v_add_f32_e32 v2, v246, v2
	v_exp_f32_e32 v250, v3
	v_sub_f32_e32 v3, v75, v81
	v_add_f32_e32 v2, v247, v2
	v_exp_f32_e32 v251, v3
	v_sub_f32_e32 v3, v76, v81
	v_add_f32_e32 v2, v248, v2
	v_exp_f32_e32 v252, v3
	v_sub_f32_e32 v3, v77, v81
	v_add_f32_e32 v2, v249, v2
	v_exp_f32_e32 v253, v3
	v_sub_f32_e32 v3, v78, v81
	v_add_f32_e32 v2, v250, v2
	v_exp_f32_e32 v219, v3
	v_sub_f32_e32 v3, v79, v81
	v_add_f32_e32 v2, v251, v2
	v_exp_f32_e32 v229, v3
	v_sub_f32_e32 v3, v80, v81
	v_add_f32_e32 v2, v252, v2
	v_exp_f32_e32 v80, v3
	v_add_f32_e32 v2, v253, v2
	v_add_f32_e32 v2, v219, v2
	v_add_f32_e32 v2, v229, v2
	v_add_f32_e32 v235, v80, v2
	ds_bpermute_b32 v236, v180, v235
	v_cvt_pk_bf16_f32 v6, v1, v51
	v_cndmask_b32_e64 v1, 0, 1, s[74:75]
	v_cvt_pk_bf16_f32 v7, v52, v53
	v_cvt_pk_bf16_f32 v8, v54, v55
	v_cvt_pk_bf16_f32 v9, v56, v57
	v_cvt_pk_bf16_f32 v2, v58, v59
	v_cvt_pk_bf16_f32 v3, v60, v61
	v_cvt_pk_bf16_f32 v4, v62, v63
	v_cvt_pk_bf16_f32 v5, v64, v65
	v_cvt_pk_bf16_f32 v76, v230, v231
	v_cvt_pk_bf16_f32 v77, v237, v238
	v_cvt_pk_bf16_f32 v78, v225, v239
	v_cvt_pk_bf16_f32 v79, v240, v241
	v_cvt_pk_bf16_f32 v72, v10, v11
	v_cvt_pk_bf16_f32 v73, v12, v13
	v_cvt_pk_bf16_f32 v74, v14, v15
	v_cvt_pk_bf16_f32 v75, v16, v17
	v_cvt_pk_bf16_f32 v68, v34, v35
	v_cvt_pk_bf16_f32 v69, v36, v37
	v_cvt_pk_bf16_f32 v70, v38, v39
	v_cvt_pk_bf16_f32 v71, v40, v41
	v_cvt_pk_bf16_f32 v64, v42, v43
	v_cvt_pk_bf16_f32 v65, v44, v45
	v_cvt_pk_bf16_f32 v66, v46, v47
	v_cvt_pk_bf16_f32 v67, v48, v49
	v_cvt_pk_bf16_f32 v60, v18, v19
	v_cvt_pk_bf16_f32 v61, v20, v21
	v_cvt_pk_bf16_f32 v62, v22, v23
	v_cvt_pk_bf16_f32 v63, v24, v25
	v_cvt_pk_bf16_f32 v56, v26, v27
	v_cvt_pk_bf16_f32 v57, v28, v29
	v_cvt_pk_bf16_f32 v58, v30, v31
	v_cvt_pk_bf16_f32 v59, v32, v33
	v_cvt_pk_bf16_f32 v52, v50, v242
	v_cvt_pk_bf16_f32 v53, v243, v244
	v_cvt_pk_bf16_f32 v54, v245, v246
	v_cvt_pk_bf16_f32 v55, v247, v248
	v_cvt_pk_bf16_f32 v48, v249, v250
	v_cvt_pk_bf16_f32 v49, v251, v252
	v_cvt_pk_bf16_f32 v50, v253, v219
	v_cvt_pk_bf16_f32 v51, v229, v80
	v_cmp_ne_u32_e64 s[72:73], 1, v1
	s_cbranch_vccnz .LBB0_203
	s_lshl_b32 s35, s27, 8
	v_add_u32_e32 v10, s35, v163
	s_add_i32 s34, s19, s31
	v_add_u32_e32 v1, s21, v164
	v_cmp_lt_i32_e32 vcc, -1, v10
	s_and_saveexec_b64 s[74:75], vcc
	s_cbranch_execz .LBB0_192
	v_lshlrev_b32_e32 v11, s43, v10
	v_add_u32_e32 v11, s34, v11
	v_lshl_add_u32 v12, v11, 10, v1
	v_mov_b32_e32 v13, v0
	v_lshl_add_u64 v[12:13], v[12:13], 1, s[94:95]
	global_load_dwordx4 v[106:109], v[12:13], off

.LBB0_203:
	v_cndmask_b32_e64 v1, 0, 1, s[86:87]
	v_cmp_ne_u32_e64 s[74:75], 1, v1
	v_or_b32_e32 v1, s25, v181
	s_andn2_b64 vcc, exec, s[86:87]
	v_add_u32_e32 v80, s30, v182
	v_lshlrev_b32_e32 v225, s43, v1
	s_cbranch_vccnz .LBB0_206
	s_add_i32 s34, s28, s20
	v_or_b32_e32 v14, s25, v165
	v_readlane_b32 s100, v254, 54
	v_lshlrev_b32_e32 v14, s43, v14
	v_readlane_b32 s101, v254, 55
	v_add_u32_e32 v14, s34, v14
	v_lshl_add_u32 v14, v14, 4, s18
	v_mov_b32_e32 v15, v0
	v_lshl_add_u64 v[14:15], v[14:15], 2, s[100:101]
	global_load_dword v237, v[14:15], off
	v_or_b32_e32 v12, 8, v1
	v_add_u32_e32 v10, s34, v225
	v_lshlrev_b32_e32 v12, s43, v12
	v_lshl_add_u32 v10, v10, 10, v80
	v_mov_b32_e32 v11, v0
	v_add_u32_e32 v12, s34, v12
	v_lshl_add_u64 v[10:11], v[10:11], 1, s[88:89]
	v_lshl_add_u32 v12, v12, 10, v80
	v_mov_b32_e32 v13, v0
	v_lshl_add_u64 v[12:13], v[12:13], 1, s[88:89]
	global_load_dwordx4 v[150:153], v[10:11], off
	global_load_dwordx4 v[146:149], v[12:13], off
	v_or_b32_e32 v10, 16, v1
	v_or_b32_e32 v1, 24, v1
	v_lshlrev_b32_e32 v1, s43, v1
	v_lshlrev_b32_e32 v10, s43, v10
	v_add_u32_e32 v1, s34, v1
	v_add_u32_e32 v10, s34, v10
	v_lshl_add_u32 v12, v1, 10, v80
	v_lshl_add_u32 v10, v10, 10, v80
	v_mov_b32_e32 v11, v0
	v_lshl_add_u64 v[10:11], v[10:11], 1, s[88:89]
	v_mov_b32_e32 v13, v0
	v_lshl_add_u64 v[12:13], v[12:13], 1, s[88:89]
	global_load_dwordx4 v[158:161], v[10:11], off
	global_load_dwordx4 v[154:157], v[12:13], off
	s_andn2_b64 vcc, exec, s[76:77]
	s_cbranch_vccnz .LBB0_207

.LBB0_213:
	s_waitcnt lgkmcnt(0)
	v_add_f32_e32 v4, v235, v236
	v_log_f32_e32 v1, v4
	s_and_b64 vcc, exec, s[74:75]
	v_add_f32_e32 v1, v81, v1
	s_cbranch_vccnz .LBB0_217
	v_max_f32_e32 v2, v1, v1
	s_waitcnt vmcnt(4)
	v_max_f32_e32 v3, v237, v237
	v_max_f32_e32 v5, v3, v2
	v_sub_f32_e32 v1, v1, v5
	v_exp_f32_e32 v2, v1
	v_sub_f32_e32 v1, v237, v5
	v_exp_f32_e32 v3, v1
	s_nop 0
	v_add_f32_e32 v1, v2, v3
	v_rcp_f32_e32 v6, v1
	v_log_f32_e32 v1, v1
	v_pk_mul_f32 v[2:3], v[2:3], v[6:7] op_sel_hi:[1,0]
	v_add_f32_e32 v1, v5, v1
	s_branch .LBB0_218

.LBB0_221:
	s_or_b64 exec, exec, s[6:7]
	ds_read_b128 v[2:5], v186
	ds_read_b128 v[6:9], v186 offset:32
	ds_read_b128 v[10:13], v186 offset:64
	ds_read_b128 v[48:51], v186 offset:96
	s_and_b64 vcc, exec, s[74:75]
	s_waitcnt lgkmcnt(3)
	v_pk_mul_f32 v[32:33], v[32:33], v[2:3]
	v_pk_mul_f32 v[16:17], v[16:17], v[2:3]
	v_cvt_pk_bf16_f32 v1, v32, v33
	v_cvt_pk_bf16_f32 v14, v16, v17
	ds_write_b16 v191, v1
	ds_write_b16_d16_hi v192, v1
	ds_write_b16 v191, v14 offset:64
	ds_write_b16_d16_hi v192, v14 offset:64
	v_pk_mul_f32 v[34:35], v[34:35], v[4:5]
	v_pk_mul_f32 v[18:19], v[18:19], v[4:5]
	v_cvt_pk_bf16_f32 v15, v34, v35
	v_cvt_pk_bf16_f32 v52, v18, v19
	ds_write_b16 v193, v15
	ds_write_b16_d16_hi v194, v15
	ds_write_b16 v193, v52 offset:64
	ds_write_b16_d16_hi v194, v52 offset:64
	s_waitcnt lgkmcnt(10)
	v_pk_mul_f32 v[36:37], v[36:37], v[6:7]
	v_pk_mul_f32 v[20:21], v[20:21], v[6:7]
	v_cvt_pk_bf16_f32 v53, v36, v37
	v_cvt_pk_bf16_f32 v54, v20, v21
	ds_write_b16 v195, v53
	ds_write_b16_d16_hi v196, v53
	ds_write_b16 v195, v54 offset:64
	ds_write_b16_d16_hi v196, v54 offset:64
	v_pk_mul_f32 v[38:39], v[38:39], v[8:9]
	v_pk_mul_f32 v[22:23], v[22:23], v[8:9]
	v_cvt_pk_bf16_f32 v55, v38, v39
	v_cvt_pk_bf16_f32 v56, v22, v23
	ds_write_b16 v197, v55
	ds_write_b16_d16_hi v198, v55
	ds_write_b16 v197, v56 offset:64
	ds_write_b16_d16_hi v198, v56 offset:64
	s_waitcnt lgkmcnt(14)
	v_pk_mul_f32 v[40:41], v[40:41], v[10:11]
	v_pk_mul_f32 v[24:25], v[24:25], v[10:11]
	v_cvt_pk_bf16_f32 v57, v40, v41
	v_cvt_pk_bf16_f32 v58, v24, v25
	ds_write_b16 v199, v57
	ds_write_b16_d16_hi v200, v57
	ds_write_b16 v199, v58 offset:64
	ds_write_b16_d16_hi v200, v58 offset:64
	v_pk_mul_f32 v[42:43], v[42:43], v[12:13]
	v_pk_mul_f32 v[26:27], v[26:27], v[12:13]
	v_cvt_pk_bf16_f32 v59, v42, v43
	v_cvt_pk_bf16_f32 v60, v26, v27
	ds_write_b16 v201, v59
	ds_write_b16_d16_hi v202, v59
	ds_write_b16 v201, v60 offset:64
	ds_write_b16_d16_hi v202, v60 offset:64
	v_pk_mul_f32 v[44:45], v[44:45], v[48:49]
	v_pk_mul_f32 v[28:29], v[28:29], v[48:49]
	v_cvt_pk_bf16_f32 v61, v44, v45
	v_cvt_pk_bf16_f32 v62, v28, v29
	ds_write_b16 v203, v61
	ds_write_b16_d16_hi v204, v61
	ds_write_b16 v203, v62 offset:64
	ds_write_b16_d16_hi v204, v62 offset:64
	v_pk_mul_f32 v[46:47], v[46:47], v[50:51]
	v_pk_mul_f32 v[30:31], v[30:31], v[50:51]
	v_cvt_pk_bf16_f32 v63, v46, v47
	v_cvt_pk_bf16_f32 v64, v30, v31
	ds_write_b16 v205, v63
	ds_write_b16_d16_hi v206, v63
	ds_write_b16 v205, v64 offset:64
	ds_write_b16_d16_hi v206, v64 offset:64
	ds_read_b128 v[2:5], v207
	s_cbranch_vccnz .LBB0_223
	ds_read_b32 v6, v187 offset:128
	s_waitcnt lgkmcnt(1)
	s_waitcnt vmcnt(3)
	v_lshlrev_b32_e32 v8, 16, v2
	v_and_b32_e32 v9, s33, v2
	v_lshlrev_b32_e32 v10, 16, v150
	v_and_b32_e32 v11, s33, v150
	v_lshlrev_b32_e32 v12, 16, v3
	v_and_b32_e32 v13, s33, v3
	v_lshlrev_b32_e32 v14, 16, v151
	v_and_b32_e32 v15, s33, v151
	v_lshlrev_b32_e32 v48, 16, v4
	v_and_b32_e32 v49, s33, v4
	v_lshlrev_b32_e32 v50, 16, v152
	v_and_b32_e32 v51, s33, v152
	v_lshlrev_b32_e32 v52, 16, v5
	v_and_b32_e32 v53, s33, v5
	v_lshlrev_b32_e32 v54, 16, v153
	v_and_b32_e32 v55, s33, v153
	s_waitcnt lgkmcnt(0)
	v_pk_fma_f32 v[8:9], v[6:7], v[10:11], v[8:9] op_sel_hi:[0,1,1]
	v_pk_fma_f32 v[12:13], v[6:7], v[14:15], v[12:13] op_sel_hi:[0,1,1]
	v_pk_fma_f32 v[48:49], v[6:7], v[50:51], v[48:49] op_sel_hi:[0,1,1]
	v_pk_fma_f32 v[52:53], v[6:7], v[54:55], v[52:53] op_sel_hi:[0,1,1]
	v_cvt_pk_bf16_f32 v2, v8, v9
	v_cvt_pk_bf16_f32 v3, v12, v13
	v_cvt_pk_bf16_f32 v4, v48, v49
	v_cvt_pk_bf16_f32 v5, v52, v53

.LBB0_225:
	v_or_b32_e32 v1, s25, v188
	v_lshlrev_b32_e32 v1, s43, v1
	v_add_u32_e32 v1, s6, v1
	v_lshl_add_u32 v6, v1, 10, v80
	v_mov_b32_e32 v7, v0
	v_lshl_add_u64 v[6:7], v[6:7], 1, s[88:89]
	s_waitcnt lgkmcnt(0)
	global_store_dwordx4 v[6:7], v[2:5], off sc1
	s_nop 1
	ds_read_b128 v[2:5], v209
	s_and_b64 vcc, exec, s[74:75]
	s_cbranch_vccnz .LBB0_227
	ds_read_b32 v6, v187 offset:192
	s_waitcnt lgkmcnt(1)
	s_waitcnt vmcnt(3)
	v_lshlrev_b32_e32 v8, 16, v2
	v_and_b32_e32 v9, s33, v2
	v_lshlrev_b32_e32 v10, 16, v158
	v_and_b32_e32 v11, s33, v158
	v_lshlrev_b32_e32 v12, 16, v3
	v_and_b32_e32 v13, s33, v3
	v_lshlrev_b32_e32 v14, 16, v159
	v_and_b32_e32 v15, s33, v159
	v_lshlrev_b32_e32 v48, 16, v4
	v_and_b32_e32 v49, s33, v4
	v_lshlrev_b32_e32 v50, 16, v160
	v_and_b32_e32 v51, s33, v160
	v_lshlrev_b32_e32 v52, 16, v5
	v_and_b32_e32 v53, s33, v5
	v_lshlrev_b32_e32 v54, 16, v161
	v_and_b32_e32 v55, s33, v161
	s_waitcnt lgkmcnt(0)
	v_pk_fma_f32 v[8:9], v[6:7], v[10:11], v[8:9] op_sel_hi:[0,1,1]
	v_pk_fma_f32 v[12:13], v[6:7], v[14:15], v[12:13] op_sel_hi:[0,1,1]
	v_pk_fma_f32 v[48:49], v[6:7], v[50:51], v[48:49] op_sel_hi:[0,1,1]
	v_pk_fma_f32 v[52:53], v[6:7], v[54:55], v[52:53] op_sel_hi:[0,1,1]
	v_cvt_pk_bf16_f32 v2, v8, v9
	v_cvt_pk_bf16_f32 v3, v12, v13
	v_cvt_pk_bf16_f32 v4, v48, v49
	v_cvt_pk_bf16_f32 v5, v52, v53
.LBB0_227:
	v_or_b32_e32 v1, s25, v189
	v_lshlrev_b32_e32 v1, s43, v1
	v_add_u32_e32 v1, s6, v1
	v_lshl_add_u32 v6, v1, 10, v80
	v_mov_b32_e32 v7, v0
	v_lshl_add_u64 v[6:7], v[6:7], 1, s[88:89]
	s_waitcnt lgkmcnt(0)
	global_store_dwordx4 v[6:7], v[2:5], off sc1
	s_nop 1
	ds_read_b128 v[2:5], v220
	s_and_b64 vcc, exec, s[74:75]
	s_cbranch_vccnz .LBB0_229
	ds_read_b32 v6, v187 offset:224
	s_waitcnt lgkmcnt(1)
	s_waitcnt vmcnt(3)
	v_lshlrev_b32_e32 v8, 16, v2
	v_and_b32_e32 v9, s33, v2
	v_lshlrev_b32_e32 v10, 16, v154
	v_and_b32_e32 v11, s33, v154
	v_lshlrev_b32_e32 v12, 16, v3
	v_and_b32_e32 v13, s33, v3
	v_lshlrev_b32_e32 v14, 16, v155
	v_and_b32_e32 v15, s33, v155
	v_lshlrev_b32_e32 v48, 16, v4
	v_and_b32_e32 v49, s33, v4
	v_lshlrev_b32_e32 v50, 16, v156
	v_and_b32_e32 v51, s33, v156
	v_lshlrev_b32_e32 v52, 16, v5
	v_and_b32_e32 v53, s33, v5
	v_lshlrev_b32_e32 v54, 16, v157
	v_and_b32_e32 v55, s33, v157
	s_waitcnt lgkmcnt(0)
	v_pk_fma_f32 v[8:9], v[6:7], v[10:11], v[8:9] op_sel_hi:[0,1,1]
	v_pk_fma_f32 v[12:13], v[6:7], v[14:15], v[12:13] op_sel_hi:[0,1,1]
	v_pk_fma_f32 v[48:49], v[6:7], v[50:51], v[48:49] op_sel_hi:[0,1,1]
	v_pk_fma_f32 v[52:53], v[6:7], v[54:55], v[52:53] op_sel_hi:[0,1,1]
	v_cvt_pk_bf16_f32 v2, v8, v9
	v_cvt_pk_bf16_f32 v3, v12, v13
	v_cvt_pk_bf16_f32 v4, v48, v49
	v_cvt_pk_bf16_f32 v5, v52, v53
.LBB0_229:
	v_or_b32_e32 v1, s25, v190
	v_lshlrev_b32_e32 v1, s43, v1
	v_add_u32_e32 v1, s6, v1
	v_lshl_add_u32 v6, v1, 10, v80
	v_mov_b32_e32 v7, v0
	v_lshl_add_u64 v[6:7], v[6:7], 1, s[88:89]
	s_waitcnt lgkmcnt(0)
	global_store_dwordx4 v[6:7], v[2:5], off sc1
	s_nop 1
	s_mov_b64 s[74:75], s[36:37]
	s_and_b64 vcc, exec, s[72:73]
	s_cbranch_vccnz .LBB0_163
	s_mov_b32 s20, s31
	s_mov_b32 s30, s21
	s_mov_b32 s18, s29
	s_mov_b32 s28, s19
	s_mov_b32 s22, s27
	s_mov_b32 s26, s24
	s_barrier
	s_waitcnt vmcnt(4)
	ds_write_b128 v167, v[82:85]
	ds_write_b128 v168, v[106:109] offset:49152
	ds_write_b128 v169, v[86:89]
	ds_write_b128 v170, v[110:113] offset:49152
	ds_write_b128 v171, v[90:93]
	ds_write_b128 v172, v[114:117] offset:49152
	ds_write_b128 v173, v[94:97]
	ds_write_b128 v174, v[118:121] offset:49152
	ds_write_b128 v175, v[98:101]
	ds_write_b128 v176, v[122:125] offset:49152
	ds_write_b128 v177, v[102:105]
	ds_write_b128 v178, v[126:129] offset:49152
	s_waitcnt lgkmcnt(0)
	s_barrier
	s_branch .LBB0_163

	.amdhsa_kernel _Z8yoco_fwd4Args
		.amdhsa_group_segment_fixed_size 0
		.amdhsa_private_segment_fixed_size 0
		.amdhsa_kernarg_size 408
		.amdhsa_user_sgpr_count 2
		.amdhsa_user_sgpr_dispatch_ptr 0
		.amdhsa_user_sgpr_queue_ptr 0
		.amdhsa_user_sgpr_kernarg_segment_ptr 1
		.amdhsa_user_sgpr_dispatch_id 0
		.amdhsa_user_sgpr_kernarg_preload_length 0
		.amdhsa_user_sgpr_kernarg_preload_offset 0
		.amdhsa_user_sgpr_private_segment_size 0
		.amdhsa_uses_dynamic_stack 0
		.amdhsa_enable_private_segment 0
		.amdhsa_system_sgpr_workgroup_id_x 1
		.amdhsa_system_sgpr_workgroup_id_y 0
		.amdhsa_system_sgpr_workgroup_id_z 0
		.amdhsa_system_sgpr_workgroup_info 0
		.amdhsa_system_vgpr_workitem_id 0
		.amdhsa_next_free_vgpr 256
		.amdhsa_next_free_sgpr 102
		.amdhsa_accum_offset 256
		.amdhsa_reserve_vcc 1
		.amdhsa_float_round_mode_32 0
		.amdhsa_float_round_mode_16_64 0
		.amdhsa_float_denorm_mode_32 3
		.amdhsa_float_denorm_mode_16_64 3
		.amdhsa_dx10_clamp 1
		.amdhsa_ieee_mode 1
		.amdhsa_fp16_overflow 0
		.amdhsa_tg_split 0
		.amdhsa_exception_fp_ieee_invalid_op 0
		.amdhsa_exception_fp_denorm_src 0
		.amdhsa_exception_fp_ieee_div_zero 0
		.amdhsa_exception_fp_ieee_overflow 0
		.amdhsa_exception_fp_ieee_underflow 0
		.amdhsa_exception_fp_ieee_inexact 0
		.amdhsa_exception_int_div_zero 0
	.end_amdhsa_kernel

amdhsa.kernels:
  - .agpr_count:     0
    .args:
      - .offset:         0
        .size:           152
        .value_kind:     by_value
      - .offset:         152
        .size:           4
        .value_kind:     hidden_block_count_x
      - .offset:         156
        .size:           4
        .value_kind:     hidden_block_count_y
      - .offset:         160
        .size:           4
        .value_kind:     hidden_block_count_z
      - .offset:         164
        .size:           2
        .value_kind:     hidden_group_size_x
      - .offset:         166
        .size:           2
        .value_kind:     hidden_group_size_y
      - .offset:         168
        .size:           2
        .value_kind:     hidden_group_size_z
      - .offset:         170
        .size:           2
        .value_kind:     hidden_remainder_x
      - .offset:         172
        .size:           2
        .value_kind:     hidden_remainder_y
      - .offset:         174
        .size:           2
        .value_kind:     hidden_remainder_z
      - .offset:         192
        .size:           8
        .value_kind:     hidden_global_offset_x
      - .offset:         200
        .size:           8
        .value_kind:     hidden_global_offset_y
      - .offset:         208
        .size:           8
        .value_kind:     hidden_global_offset_z
      - .offset:         216
        .size:           2
        .value_kind:     hidden_grid_dims
      - .offset:         272
        .size:           4
        .value_kind:     hidden_dynamic_lds_size
    .group_segment_fixed_size: 0
    .kernarg_segment_align: 8
    .kernarg_segment_size: 408
    .language:       OpenCL C
    .language_version:
      - 2
      - 0
    .max_flat_workgroup_size: 512
    .name:           _Z8yoco_fwd4Args
    .private_segment_fixed_size: 0
    .sgpr_count:     108
    .sgpr_spill_count: 124
    .symbol:         _Z8yoco_fwd4Args.kd
    .uniform_work_group_size: 1
    .uses_dynamic_stack: false
    .vgpr_count:     256
    .vgpr_spill_count: 0
    .wavefront_size: 64
